# v32 + mixer phases: streaming units (decode retention, scan, weight conversion) keep XCD-striped ids, data-sharing units keep XCD-contiguous ids
# baseline (speedup 1.0000x reference)
; #define LAS __attribute__((address_space(3)))
; DI float bf2f(unsigned short u) { return __uint_as_float(((unsigned)u) << 16); }
; DI float gamma_of(int h) { return 1.0f - exp2f(-5.0f - (float)h); }
; DI void ret_decode_unit(LAS unsigned char* lds, const bf16_t* Z, const float* S0, float* S1, bf16_t* MIX, const float* rng, int b, int h, int tid) {
;     LAS float* qv = (LAS float*)lds; LAS float* red = qv + 768;
;     const int lane = tid & 63, wid = tid >> 6;
;     const bf16_t* zrow = Z + (size_t)(LP + b) * INW;
;     if (tid < 256) { qv[tid] = bf2f(zrow[C_RQ + h * 256 + tid]); qv[256 + tid] = bf2f(zrow[C_RK + h * 256 + tid]); qv[512 + tid] = bf2f(zrow[C_RV + h * 256 + tid]); }
;     __syncthreads();
;     const float gm = gamma_of(h);
;     const f32x4 v4 = *(const LAS f32x4*)(qv + 512 + 4 * lane);
;     f32x4 acc = {0.f, 0.f, 0.f, 0.f};
;     const size_t off = ((size_t)(b * 4 + h) * 256 + wid * 32) * 256 + 4 * lane;
;     const float* s0 = S0 + off; float* s1 = S1 + off;
; __global__ void __launch_bounds__(512, 2) fwd_kernel(Args a) {
;     ...
;     if (IN(2)) for (int rep_ = 0; rep_ < 1 + ((DUPMASK >> 2) & 1); ++rep_) { if (rep_) xcd_barrier(bar);
;         if (bx & 1) for (int u = bx; u < 256; u += G) ret_decode_unit(lds, Z, state0, out + O_SS, MIX, rng, u >> 2, u & 3, tid);
;         for (int u = bx; u < 256; u += G) ret_step1(lds, Z, KV, u >> 2, u & 3, tid);
;         if (!(bx & 1)) for (int u = bx; u < 256; u += G) ret_decode_unit(lds, Z, state0, out + O_SS, MIX, rng, u >> 2, u & 3, tid);
;     }
.LBB0_226:
	s_mov_b32 s32, s92
	s_and_b32 s98, s92, 7
	s_lshl_b32 s98, s98, 5
	s_lshr_b32 s99, s92, 3
	s_or_b32 s92, s98, s99
	s_cmp_lt_i32 s62, 3
	s_cselect_b64 s[2:3], -1, 0
	s_add_u32 s56, s60, 0x8000000
	s_addc_u32 s57, s61, 0
	s_add_u32 s4, s60, 0xfc00000
	s_addc_u32 s5, s61, 0
	v_writelane_b32 v254, s4, 23
	s_and_b64 s[10:11], s[2:3], s[0:1]
	s_andn2_b64 vcc, exec, s[10:11]
	v_writelane_b32 v254, s5, 24
	v_lshrrev_b32_e32 v252, 6, v253
	v_cmp_gt_u32_e64 s[0:1], 64, v253
	s_cbranch_vccnz .LBB0_250
	s_bitcmp0_b32 s92, 0
	v_readlane_b32 s68, v254, 7
	s_cselect_b64 s[14:15], -1, 0
	s_cmpk_gt_i32 s92, 0xff
	v_readlane_b32 s82, v254, 21
	v_lshlrev_b32_e32 v0, 2, v253
	s_cselect_b64 s[2:3], -1, 0
	v_readlane_b32 s83, v254, 22
	s_add_u32 s12, s82, 0x5220000
	v_and_b32_e32 v147, 0xfc, v0
	v_readlane_b32 s72, v254, 11
	v_readlane_b32 s73, v254, 12
	s_addc_u32 s13, s83, 0
	s_movk_i32 s4, 0x100
	v_add_u32_e32 v146, 0, v0
	v_lshlrev_b32_e32 v20, 2, v147
	v_mov_b32_e32 v21, 0
	v_lshl_add_u32 v149, v252, 7, 0
	v_mul_u32_u24_e32 v0, 0x380, v252
	s_or_b64 s[2:3], s[14:15], s[2:3]
	s_mov_b32 s17, 0
	v_add_u32_e32 v144, 0x900, v253
	v_add_u32_e32 v145, 0xd00, v253
	v_cmp_gt_u32_e64 s[6:7], s4, v253
	v_add_u32_e32 v148, 0, v20
	v_lshl_or_b32 v128, v252, 13, v147
	v_mov_b32_e32 v129, v21
	v_add3_u32 v150, v149, v0, v20
	v_lshl_add_u64 v[130:131], s[72:73], 0, v[20:21]
	s_and_b64 vcc, exec, s[2:3]
	v_readlane_b32 s69, v254, 8
	v_readlane_b32 s70, v254, 9
	v_readlane_b32 s71, v254, 10
	v_readlane_b32 s74, v254, 13
	v_readlane_b32 s75, v254, 14
	v_readlane_b32 s76, v254, 15
	v_readlane_b32 s77, v254, 16
	v_readlane_b32 s78, v254, 17
	v_readlane_b32 s79, v254, 18
	v_readlane_b32 s80, v254, 19
	v_readlane_b32 s81, v254, 20
	s_cbranch_vccnz .LBB0_236
	v_mbcnt_lo_u32_b32 v0, -1, 0
	v_mov_b32_e32 v30, 0x42800000
	v_mov_b32_e32 v31, 0x358637bd
	v_mbcnt_hi_u32_b32 v32, -1, v0
	s_mov_b32 s18, s32
	s_branch .LBB0_230

; #define LAS __attribute__((address_space(3)))
; DI float bf2f(unsigned short u) { return __uint_as_float(((unsigned)u) << 16); }
; DI float gamma_of(int h) { return 1.0f - exp2f(-5.0f - (float)h); }
; DI void ret_decode_unit(LAS unsigned char* lds, const bf16_t* Z, const float* S0, float* S1, bf16_t* MIX, const float* rng, int b, int h, int tid) {
;     LAS float* qv = (LAS float*)lds; LAS float* red = qv + 768;
;     const int lane = tid & 63, wid = tid >> 6;
;     const bf16_t* zrow = Z + (size_t)(LP + b) * INW;
;     if (tid < 256) { qv[tid] = bf2f(zrow[C_RQ + h * 256 + tid]); qv[256 + tid] = bf2f(zrow[C_RK + h * 256 + tid]); qv[512 + tid] = bf2f(zrow[C_RV + h * 256 + tid]); }
;     __syncthreads();
;     const float gm = gamma_of(h);
;     const f32x4 v4 = *(const LAS f32x4*)(qv + 512 + 4 * lane);
;     f32x4 acc = {0.f, 0.f, 0.f, 0.f};
;     const size_t off = ((size_t)(b * 4 + h) * 256 + wid * 32) * 256 + 4 * lane;
;     const float* s0 = S0 + off; float* s1 = S1 + off;
; __global__ void __launch_bounds__(512, 2) fwd_kernel(Args a) {
;     ...
;         if (bx & 1) for (int u = bx; u < 256; u += G) ret_decode_unit(lds, Z, state0, out + O_SS, MIX, rng, u >> 2, u & 3, tid);
;         for (int u = bx; u < 256; u += G) ret_step1(lds, Z, KV, u >> 2, u & 3, tid);
;         if (!(bx & 1)) for (int u = bx; u < 256; u += G) ret_decode_unit(lds, Z, state0, out + O_SS, MIX, rng, u >> 2, u & 3, tid);
.LBB0_241:
	s_and_b64 s[2:3], s[16:17], s[14:15]
	s_andn2_b64 vcc, exec, s[2:3]
	s_cbranch_vccnz .LBB0_250
	v_mbcnt_lo_u32_b32 v0, -1, 0
	v_mov_b32_e32 v30, 0x42800000
	s_mov_b32 s15, 0
	v_mov_b32_e32 v31, 0x358637bd
	v_mov_b32_e32 v21, 0
	v_mbcnt_hi_u32_b32 v32, -1, v0
	s_mov_b32 s16, s32
	s_branch .LBB0_244

; DI void ret_scan(const bf16_t* KV, bf16_t* SP, float* o_state, int gt, int nthreads) {
;     for (int e = gt; e < 65536; e += nthreads) {
;         const int h = e >> 14, dv = (e >> 6) & 255, dk4 = (e & 63) * 4;
;         const float lg = log1pf(-exp2f(-5.0f - (float)h)), Dc = __expf(128.0f * lg), c1 = __expf(127.0f * lg);
;         const size_t base = ((size_t)(h * 256 + dv)) * 256 + dk4;
; __global__ void __launch_bounds__(512, 2) fwd_kernel(Args a) {
;     ...
;     if (IN(3)) for (int rep_ = 0; rep_ < 1 + ((DUPMASK >> 3) & 1); ++rep_) { if (rep_) xcd_barrier(bar);
;         if (tid < 256) ret_scan(KV, SP, out + O_SP, bx * 256 + tid, G * 256);
;         if (bx & 1) for (int u = bx; u < 256; u += G) attn_decode_unit(lds, Z, cache_k, cache_v, MIX, gq, gk, sinks, out + O_KS, out + O_VS, u >> 1, u & 1, tid);
.LBB0_304:
	s_cmp_lt_i32 s62, 4
	s_cselect_b64 s[2:3], -1, 0
	s_add_u32 s4, s60, 0x13c00000
	s_addc_u32 s5, s61, 0
	v_writelane_b32 v254, s4, 25
	s_and_b64 s[24:25], s[2:3], s[0:1]
	s_andn2_b64 vcc, exec, s[24:25]
	v_writelane_b32 v254, s5, 26
	v_writelane_b32 v254, s84, 27
	s_nop 1
	v_writelane_b32 v254, s85, 28
	v_writelane_b32 v254, s86, 29
	s_nop 1
	v_writelane_b32 v254, s87, 30
	v_writelane_b32 v254, s88, 31
	s_nop 1
	v_writelane_b32 v254, s89, 32
	s_cbranch_vccnz .LBB0_349
	v_writelane_b32 v254, s24, 33
	s_movk_i32 s0, 0x100
	v_cmp_gt_u32_e64 s[2:3], s0, v253
	v_writelane_b32 v254, s25, 34
	v_writelane_b32 v254, s90, 35
	s_mov_b32 s0, s92
	v_lshl_add_u32 v84, s32, 8, v253
	v_writelane_b32 v254, s91, 36
	v_writelane_b32 v254, s0, 37
	s_nop 1
	v_writelane_b32 v254, s1, 38
	s_mov_b32 s0, 0x10000
	v_cmp_gt_i32_e32 vcc, s0, v84
	s_and_b64 s[0:1], s[2:3], vcc
	s_mov_b64 s[4:5], exec
	v_writelane_b32 v254, s4, 39
	s_and_b64 s[0:1], s[4:5], s[0:1]
	s_nop 0
	v_writelane_b32 v254, s5, 40
	s_mov_b64 exec, s[0:1]
	s_cbranch_execz .LBB0_310
	v_readlane_b32 s4, v254, 7
	v_readlane_b32 s10, v254, 13
	v_readlane_b32 s18, v254, 21
	v_readlane_b32 s11, v254, 14
	v_readlane_b32 s14, v254, 17
	v_readlane_b32 s15, v254, 18
	v_readlane_b32 s17, v254, 20
	v_readlane_b32 s19, v254, 22
	s_add_u32 s10, s18, 0x4120000
	s_addc_u32 s11, s19, 0
	s_lshl_b32 s33, s64, 8
	s_mov_b64 s[14:15], 0
	v_mov_b32_e32 v85, 0x42800000
	v_not_b32_e32 v86, 63
	v_mov_b32_e32 v87, 0x3ecc95a3
	v_mov_b32_e32 v88, 0x7fc00000
	v_mov_b32_e32 v89, 0xff800000
	s_mov_b32 s17, 0
	v_mov_b32_e32 v1, 0
	v_mov_b32_e32 v2, 0x3f317218
	v_readlane_b32 s5, v254, 8
	v_readlane_b32 s6, v254, 9
	v_readlane_b32 s7, v254, 10
	v_readlane_b32 s8, v254, 11
	v_readlane_b32 s9, v254, 12
	v_readlane_b32 s12, v254, 15
	v_readlane_b32 s13, v254, 16
	v_readlane_b32 s16, v254, 19

; #define LAS __attribute__((address_space(3)))
; DI float bf2f(unsigned short u) { return __uint_as_float(((unsigned)u) << 16); }
; DI float gamma_of(int h) { return 1.0f - exp2f(-5.0f - (float)h); }
; DI void ret_decode_unit(LAS unsigned char* lds, const bf16_t* Z, const float* S0, float* S1, bf16_t* MIX, const float* rng, int b, int h, int tid) {
;     LAS float* qv = (LAS float*)lds; LAS float* red = qv + 768;
;     const int lane = tid & 63, wid = tid >> 6;
;     const bf16_t* zrow = Z + (size_t)(LP + b) * INW;
;     if (tid < 256) { qv[tid] = bf2f(zrow[C_RQ + h * 256 + tid]); qv[256 + tid] = bf2f(zrow[C_RK + h * 256 + tid]); qv[512 + tid] = bf2f(zrow[C_RV + h * 256 + tid]); }
;     __syncthreads();
;     const float gm = gamma_of(h);
;     const f32x4 v4 = *(const LAS f32x4*)(qv + 512 + 4 * lane);
;     f32x4 acc = {0.f, 0.f, 0.f, 0.f};
;     const size_t off = ((size_t)(b * 4 + h) * 256 + wid * 32) * 256 + 4 * lane;
;     const float* s0 = S0 + off; float* s1 = S1 + off;
; __global__ void __launch_bounds__(512, 2) fwd_kernel(Args a) {
;     ...
;         if (bx & 1) for (int u = bx; u < 256; u += G) attn_decode_unit(lds, Z, cache_k, cache_v, MIX, gq, gk, sinks, out + O_KS, out + O_VS, u >> 1, u & 1, tid);
;         for (int u = 256 + bx; u < 512; u += G) ret_decode_unit(lds, Z, state0, out + O_SS, MIX, rng, u >> 2, u & 3, tid);
.LBB0_325:
	s_cmpk_lt_i32 s92, 0x100
	s_cselect_b64 s[20:21], -1, 0
	s_cmpk_gt_i32 s92, 0xff
	s_cbranch_scc1 .LBB0_334
	v_readlane_b32 s68, v254, 7
	s_add_i32 s22, s32, 0x100
	v_readlane_b32 s82, v254, 21
	v_lshlrev_b32_e32 v26, 2, v62
	v_lshl_add_u32 v65, v252, 7, 0
	v_mul_u32_u24_e32 v0, 0x380, v252
	v_readlane_b32 s72, v254, 11
	v_readlane_b32 s73, v254, 12
	v_readlane_b32 s83, v254, 22
	s_add_u32 s24, s82, 0x5220000
	v_mov_b32_e32 v27, 0
	v_add3_u32 v66, v65, v0, v26
	v_mbcnt_lo_u32_b32 v0, -1, 0
	v_add_u32_e32 v25, 0x900, v253
	v_add_u32_e32 v63, 0xd00, v253
	s_addc_u32 s25, s83, 0
	s_mov_b32 s27, 0
	v_add_u32_e32 v64, 0, v26
	v_lshl_or_b32 v28, v252, 13, v62
	v_mov_b32_e32 v29, v27
	v_lshl_add_u64 v[30:31], s[72:73], 0, v[26:27]
	v_mov_b32_e32 v67, 0x42800000
	v_mov_b32_e32 v68, 0x358637bd
	v_mbcnt_hi_u32_b32 v69, -1, v0
	v_readlane_b32 s69, v254, 8
	v_readlane_b32 s70, v254, 9
	v_readlane_b32 s71, v254, 10
	v_readlane_b32 s74, v254, 13
	v_readlane_b32 s75, v254, 14
	v_readlane_b32 s76, v254, 15
	v_readlane_b32 s77, v254, 16
	v_readlane_b32 s78, v254, 17
	v_readlane_b32 s79, v254, 18
	v_readlane_b32 s80, v254, 19
	v_readlane_b32 s81, v254, 20
	s_branch .LBB0_328

; #define LAS __attribute__((address_space(3)))
; template <class Resolve>
; DI void p0_convert(const Resolve R, int first, int stride, int total, LAS float* scr, int lane) {
;     for (int it = first; it < total; it += 2 * stride) {
;         const bool two = it + stride < total;
; __global__ void __launch_bounds__(512, 2) fwd_kernel(Args a) {
;     ...
;         {
;             LAS float* scr = (LAS float*)(lds + wid * 17408);
;             p0_convert(ResRest{w_out, w_up, w_dn, WOUT, WUP, WDN, ln2_g}, bx * 8 + wid, G * 8, NP0_REST, scr, lane);
;         }
.LBB0_437:
	s_lshl_b32 s0, s32, 3
	v_readlane_b32 s1, v254, 6
	s_add_i32 s20, s1, s0
	v_readlane_b32 s30, v254, 41
	s_cmpk_gt_i32 s20, 0x23ff
	v_readlane_b32 s31, v254, 42
	s_cbranch_scc1 .LBB0_457
	v_readlane_b32 s0, v254, 6
	s_mulk_i32 s0, 0x4400
	v_lshlrev_b32_e32 v0, 2, v253
	s_add_i32 s0, s0, 0
	v_lshrrev_b32_e32 v72, 3, v152
	v_and_b32_e32 v0, 28, v0
	v_and_b32_e32 v1, 7, v253
	v_mov_b32_e32 v65, 0
	v_lshl_add_u32 v3, v1, 4, s0
	v_mul_u32_u24_e32 v4, 0x84, v72
	v_lshlrev_b32_e32 v2, 3, v1
	v_mul_u32_u24_e32 v1, 0x420, v1
	v_lshlrev_b32_e32 v5, 2, v72
	v_lshlrev_b32_e32 v66, 2, v0
	s_lshl_b32 s21, s64, 3
	v_or_b32_e32 v73, 8, v72
	v_or_b32_e32 v74, 16, v72
	v_or_b32_e32 v75, 24, v72
	v_add3_u32 v76, s0, v1, v5
	s_lshl_b32 s22, s64, 4
	v_mov_b32_e32 v68, v66
	v_mov_b32_e32 v69, v65
	v_lshlrev_b32_e32 v64, 1, v2
	v_add_u32_e32 v77, v3, v4
	s_branch .LBB0_440
